# pass-C item: the eight output-gate / head-gain loads of the item tail are issued with the item's other loads (spare VGPRs), tail uses copies; on top of mixing wait fixes
# speedup vs baseline: 1.0054x; 1.0016x over previous
.LBB0_530:
	v_or_b32_e32 v182, s52, v122
	v_mov_b64_e32 v[184:185], s[4:5]
	v_mov_b32_e32 v183, 0x1c00
	s_mul_i32 s100, s53, 0x1c00
	v_mad_u64_u32 v[184:185], vcc, v182, v183, v[184:185]
	s_lshl_b32 s101, s97, 2
	v_add_u32_e32 v185, s100, v185
	v_lshl_add_u64 v[184:185], v[184:185], 0, s[90:91]
	v_readlane_b32 s100, v255, 17
	v_lshlrev_b64 v[192:193], 1, v[126:127]
	v_lshlrev_b64 v[194:195], 1, v[128:129]
	s_add_u32 s100, s100, s101
	v_readlane_b32 s101, v255, 18
	v_lshlrev_b64 v[196:197], 1, v[124:125]
	v_add_co_u32_e32 v184, vcc, 0x1800, v184
	s_addc_u32 s101, s101, 0
	s_nop 0
	v_addc_co_u32_e32 v185, vcc, 0, v185, vcc
	v_lshl_add_u64 v[192:193], v[184:185], 0, v[192:193]
	v_lshl_add_u64 v[194:195], v[184:185], 0, v[194:195]
	v_lshl_add_u64 v[196:197], v[184:185], 0, v[196:197]
	global_load_dwordx2 v[92:93], v[192:193], off
	global_load_dwordx2 v[94:95], v[194:195], off offset:32
	global_load_dwordx2 v[96:97], v[194:195], off offset:64
	global_load_dwordx2 v[98:99], v[196:197], off
	v_lshl_add_u64 v[192:193], v[126:127], 2, s[100:101]
	v_lshl_add_u64 v[194:195], v[128:129], 2, s[100:101]
	v_lshl_add_u64 v[196:197], v[124:125], 2, s[100:101]
	global_load_dwordx4 v[224:227], v[192:193], off
	global_load_dwordx4 v[228:231], v[194:195], off offset:64
	global_load_dwordx4 v[232:235], v[194:195], off offset:128
	global_load_dwordx4 v[236:239], v[196:197], off
	s_waitcnt vmcnt(24)
	ds_write2st64_b32 v144, v79, v80 offset1:8
	s_and_saveexec_b64 s[14:15], s[58:59]
	ds_write_b32 v144, v78 offset:4096
	s_or_b64 exec, exec, s[14:15]
	s_waitcnt lgkmcnt(0)
	s_barrier
	s_mov_b64 s[14:15], exec
	v_readlane_b32 s16, v254, 55
	v_readlane_b32 s17, v254, 56
	s_and_b64 s[16:17], s[14:15], s[16:17]
	s_mov_b64 exec, s[16:17]
	s_cbranch_execz .LBB0_534
	v_mov_b32_e32 v78, 0x3f803f80
	s_nop 0
	v_mov_b32_e32 v79, v78
	v_mov_b32_e32 v80, v78
	v_mov_b32_e32 v81, v78
	ds_write_b128 v145, v[78:81] offset:35072
.LBB0_534:
	s_or_b64 exec, exec, s[14:15]
	s_waitcnt vmcnt(9)
	ds_write_b128 v146, v[72:75] offset:34816
	s_waitcnt vmcnt(8)
	ds_write_b128 v146, v[68:71] offset:34832
	s_mov_b64 s[14:15], exec
	v_readlane_b32 s16, v254, 47
	v_readlane_b32 s17, v254, 48
	s_and_b64 s[16:17], s[14:15], s[16:17]
	s_mov_b64 exec, s[16:17]
	ds_write_b128 v166, v[44:47] offset:54272
	s_or_b64 exec, exec, s[14:15]
	s_mov_b64 s[14:15], exec
	v_readlane_b32 s16, v254, 49
	v_readlane_b32 s17, v254, 50
	s_and_b64 s[16:17], s[14:15], s[16:17]
	s_mov_b64 exec, s[16:17]
	ds_write_b128 v167, v[40:43] offset:54272
	s_or_b64 exec, exec, s[14:15]
	s_mov_b64 s[14:15], exec
	v_readlane_b32 s16, v254, 51
	v_readlane_b32 s17, v254, 52
	s_and_b64 s[16:17], s[14:15], s[16:17]
	s_mov_b64 exec, s[16:17]
	ds_write_b128 v168, v[56:59] offset:54272
	s_or_b64 exec, exec, s[14:15]
	s_mov_b64 s[14:15], exec
	v_readlane_b32 s16, v254, 53
	v_readlane_b32 s17, v254, 54
	s_and_b64 s[16:17], s[14:15], s[16:17]
	s_mov_b64 exec, s[16:17]
	ds_write_b128 v169, v[48:51] offset:54272
	s_or_b64 exec, exec, s[14:15]
	s_and_saveexec_b64 s[14:15], s[58:59]
	ds_write_b128 v170, v[64:67] offset:54272
	s_or_b64 exec, exec, s[14:15]
	ds_read_b128 v[40:43], v147
	ds_read_b128 v[44:47], v147 offset:16
	ds_read_b128 v[48:51], v148
	ds_read_b128 v[56:59], v148 offset:16
	v_lshlrev_b32_e32 v64, 16, v52
	v_and_b32_e32 v65, 0xffff0000, v52
	v_lshlrev_b32_e32 v52, 16, v53
	v_and_b32_e32 v53, 0xffff0000, v53
	s_waitcnt lgkmcnt(1)
	v_pk_fma_f32 v[48:49], v[48:49], v[64:65], v[40:41]
	v_pk_fma_f32 v[50:51], v[50:51], v[52:53], v[42:43]
	v_lshlrev_b32_e32 v40, 16, v54
	v_and_b32_e32 v41, 0xffff0000, v54
	v_lshlrev_b32_e32 v42, 16, v55
	v_and_b32_e32 v43, 0xffff0000, v55
	s_waitcnt lgkmcnt(0)
	v_pk_fma_f32 v[52:53], v[56:57], v[40:41], v[44:45]
	v_pk_fma_f32 v[54:55], v[58:59], v[42:43], v[46:47]
	ds_read_b128 v[44:47], v148 offset:512
	v_lshlrev_b32_e32 v40, 16, v60
	v_and_b32_e32 v41, 0xffff0000, v60
	v_lshlrev_b32_e32 v42, 16, v61
	v_and_b32_e32 v43, 0xffff0000, v61
	s_waitcnt lgkmcnt(0)
	v_pk_fma_f32 v[56:57], v[46:47], v[42:43], v[50:51]
	v_pk_fma_f32 v[58:59], v[44:45], v[40:41], v[48:49]
	ds_read_b128 v[48:51], v148 offset:528
	v_lshlrev_b32_e32 v44, 16, v62
	v_and_b32_e32 v45, 0xffff0000, v62
	v_lshlrev_b32_e32 v46, 16, v63
	v_and_b32_e32 v47, 0xffff0000, v63
	s_waitcnt lgkmcnt(0)
	v_pk_fma_f32 v[60:61], v[50:51], v[46:47], v[54:55]
	v_pk_fma_f32 v[62:63], v[48:49], v[44:45], v[52:53]
	ds_read_b128 v[52:55], v148 offset:1024
	v_lshlrev_b32_e32 v48, 16, v36
	v_and_b32_e32 v49, 0xffff0000, v36
	v_lshlrev_b32_e32 v50, 16, v37
	v_and_b32_e32 v51, 0xffff0000, v37
	s_waitcnt lgkmcnt(0)
	v_pk_fma_f32 v[64:65], v[52:53], v[48:49], v[58:59]
	v_pk_fma_f32 v[66:67], v[54:55], v[50:51], v[56:57]
	ds_read_b128 v[52:55], v148 offset:1040
	v_lshlrev_b32_e32 v36, 16, v38
	v_and_b32_e32 v37, 0xffff0000, v38
	v_lshlrev_b32_e32 v38, 16, v39
	v_and_b32_e32 v39, 0xffff0000, v39
	s_waitcnt lgkmcnt(0)
	v_pk_fma_f32 v[68:69], v[54:55], v[38:39], v[60:61]
	ds_read_b128 v[58:61], v148 offset:1536
	v_lshlrev_b32_e32 v54, 16, v32
	v_and_b32_e32 v55, 0xffff0000, v32
	v_lshlrev_b32_e32 v56, 16, v33
	v_and_b32_e32 v57, 0xffff0000, v33
	s_waitcnt lgkmcnt(0)
	v_pk_fma_f32 v[66:67], v[60:61], v[56:57], v[66:67]
	v_pk_fma_f32 v[64:65], v[58:59], v[54:55], v[64:65]
	ds_read_b128 v[58:61], v148 offset:1552
	v_lshlrev_b32_e32 v32, 16, v35
	v_and_b32_e32 v33, 0xffff0000, v35
	v_pk_fma_f32 v[62:63], v[52:53], v[36:37], v[62:63]
	v_lshlrev_b32_e32 v52, 16, v34
	v_and_b32_e32 v53, 0xffff0000, v34
	s_waitcnt lgkmcnt(0)
	v_pk_fma_f32 v[34:35], v[60:61], v[32:33], v[68:69]
	v_mul_f32_e32 v60, 0xbfb8aa3b, v64
	v_mul_f32_e32 v61, 0xbfb8aa3b, v65
	v_exp_f32_e32 v60, v60
	v_exp_f32_e32 v61, v61
	v_pk_fma_f32 v[58:59], v[58:59], v[52:53], v[62:63]
	s_mov_b32 s14, 0x3db504f3
	v_add_f32_e32 v60, 1.0, v60
	v_add_f32_e32 v61, 1.0, v61
	v_rcp_f32_e32 v60, v60
	v_rcp_f32_e32 v61, v61
	v_mul_f32_e32 v62, 0xbfb8aa3b, v66
	v_mul_f32_e32 v63, 0xbfb8aa3b, v67
	v_exp_f32_e32 v62, v62
	v_pk_mul_f32 v[60:61], v[64:65], v[60:61]
	v_mul_f32_e32 v64, 0xbfb8aa3b, v58
	v_mul_f32_e32 v65, 0xbfb8aa3b, v59
	v_exp_f32_e32 v64, v64
	v_exp_f32_e32 v65, v65
	v_exp_f32_e32 v63, v63
	v_add_f32_e32 v62, 1.0, v62
	v_add_f32_e32 v64, 1.0, v64
	v_add_f32_e32 v65, 1.0, v65
	v_rcp_f32_e32 v64, v64
	v_rcp_f32_e32 v65, v65
	v_add_f32_e32 v63, 1.0, v63
	v_rcp_f32_e32 v62, v62
	v_rcp_f32_e32 v63, v63
	v_pk_mul_f32 v[58:59], v[58:59], v[64:65]
	v_pk_mul_f32 v[60:61], v[60:61], s[14:15] op_sel_hi:[1,0]
	v_pk_mul_f32 v[64:65], v[58:59], s[14:15] op_sel_hi:[1,0]
	v_mul_f32_e32 v58, 0xbfb8aa3b, v34
	v_mul_f32_e32 v59, 0xbfb8aa3b, v35
	v_exp_f32_e32 v58, v58
	v_exp_f32_e32 v59, v59
	v_pk_mul_f32 v[62:63], v[66:67], v[62:63]
	s_and_b64 vcc, exec, s[12:13]
	v_add_f32_e32 v58, 1.0, v58
	v_add_f32_e32 v59, 1.0, v59
	v_rcp_f32_e32 v58, v58
	v_rcp_f32_e32 v59, v59
	v_pk_mul_f32 v[62:63], v[62:63], s[14:15] op_sel_hi:[1,0]
	v_pk_mul_f32 v[34:35], v[34:35], v[58:59]
	s_nop 0
	v_pk_mul_f32 v[34:35], v[34:35], s[14:15] op_sel_hi:[1,0]
	v_cvt_pk_bf16_f32 v58, v60, v61
	v_cvt_pk_bf16_f32 v59, v62, v63
	v_cvt_pk_bf16_f32 v60, v64, v65
	v_cvt_pk_bf16_f32 v61, v34, v35
	ds_write_b128 v171, v[58:61]
	ds_read_b128 v[58:61], v147
	ds_read_b128 v[62:65], v147 offset:16
	ds_read_b128 v[66:69], v148
	ds_read_b128 v[70:73], v148 offset:16
	s_waitcnt lgkmcnt(1)
	v_pk_fma_f32 v[34:35], v[66:67], v[40:41], v[58:59]
	v_pk_fma_f32 v[58:59], v[68:69], v[42:43], v[60:61]
	ds_read_b128 v[40:43], v148 offset:512
	s_waitcnt lgkmcnt(1)
	v_pk_fma_f32 v[44:45], v[70:71], v[44:45], v[62:63]
	v_pk_fma_f32 v[46:47], v[72:73], v[46:47], v[64:65]
	s_waitcnt lgkmcnt(0)
	v_pk_fma_f32 v[50:51], v[42:43], v[50:51], v[58:59]
	v_pk_fma_f32 v[48:49], v[40:41], v[48:49], v[34:35]
	ds_read_b128 v[40:43], v148 offset:528
	s_waitcnt lgkmcnt(0)
	v_pk_fma_f32 v[40:41], v[40:41], v[36:37], v[44:45]
	ds_read_b128 v[34:37], v148 offset:1024
	v_pk_fma_f32 v[38:39], v[42:43], v[38:39], v[46:47]
	s_waitcnt lgkmcnt(0)
	v_pk_fma_f32 v[42:43], v[34:35], v[54:55], v[48:49]
	v_pk_fma_f32 v[44:45], v[36:37], v[56:57], v[50:51]
	ds_read_b128 v[34:37], v148 offset:1040
	s_waitcnt lgkmcnt(0)
	v_pk_fma_f32 v[40:41], v[34:35], v[52:53], v[40:41]
	v_pk_fma_f32 v[36:37], v[36:37], v[32:33], v[38:39]
	ds_read_b128 v[32:35], v148 offset:1536
	v_lshlrev_b32_e32 v38, 16, v28
	v_and_b32_e32 v39, 0xffff0000, v28
	v_lshlrev_b32_e32 v28, 16, v29
	v_and_b32_e32 v29, 0xffff0000, v29
	s_waitcnt lgkmcnt(0)
	v_pk_fma_f32 v[34:35], v[34:35], v[28:29], v[44:45]
	v_pk_fma_f32 v[32:33], v[32:33], v[38:39], v[42:43]
	v_lshlrev_b32_e32 v38, 16, v30
	v_and_b32_e32 v39, 0xffff0000, v30
	v_lshlrev_b32_e32 v42, 16, v31
	v_and_b32_e32 v43, 0xffff0000, v31
	ds_read_b128 v[28:31], v148 offset:1552
	v_lshlrev_b32_e32 v44, 16, v24
	v_and_b32_e32 v45, 0xffff0000, v24
	v_lshlrev_b32_e32 v24, 16, v25
	v_and_b32_e32 v25, 0xffff0000, v25
	s_waitcnt lgkmcnt(0)
	v_pk_fma_f32 v[30:31], v[30:31], v[42:43], v[36:37]
	v_mul_f32_e32 v36, 0xbfb8aa3b, v32
	v_mul_f32_e32 v37, 0xbfb8aa3b, v33
	v_exp_f32_e32 v36, v36
	v_exp_f32_e32 v37, v37
	v_pk_fma_f32 v[28:29], v[28:29], v[38:39], v[40:41]
	v_add_f32_e32 v36, 1.0, v36
	v_add_f32_e32 v37, 1.0, v37
	v_rcp_f32_e32 v36, v36
	v_rcp_f32_e32 v37, v37
	s_nop 0
	v_pk_mul_f32 v[32:33], v[32:33], v[36:37]
	v_mul_f32_e32 v36, 0xbfb8aa3b, v34
	v_mul_f32_e32 v37, 0xbfb8aa3b, v35
	v_exp_f32_e32 v36, v36
	v_exp_f32_e32 v37, v37
	v_pk_mul_f32 v[32:33], v[32:33], s[14:15] op_sel_hi:[1,0]
	v_add_f32_e32 v36, 1.0, v36
	v_add_f32_e32 v37, 1.0, v37
	v_rcp_f32_e32 v36, v36
	v_rcp_f32_e32 v37, v37
	s_nop 0
	v_pk_mul_f32 v[34:35], v[34:35], v[36:37]
	v_mul_f32_e32 v36, 0xbfb8aa3b, v28
	v_mul_f32_e32 v37, 0xbfb8aa3b, v29
	v_exp_f32_e32 v36, v36
	v_exp_f32_e32 v37, v37
	v_pk_mul_f32 v[34:35], v[34:35], s[14:15] op_sel_hi:[1,0]
	v_add_f32_e32 v36, 1.0, v36
	v_add_f32_e32 v37, 1.0, v37
	v_rcp_f32_e32 v36, v36
	v_rcp_f32_e32 v37, v37
	s_nop 0
	v_pk_mul_f32 v[28:29], v[28:29], v[36:37]
	s_nop 0
	v_pk_mul_f32 v[36:37], v[28:29], s[14:15] op_sel_hi:[1,0]
	v_mul_f32_e32 v28, 0xbfb8aa3b, v30
	v_mul_f32_e32 v29, 0xbfb8aa3b, v31
	v_exp_f32_e32 v28, v28
	v_exp_f32_e32 v29, v29
	v_add_f32_e32 v28, 1.0, v28
	v_add_f32_e32 v29, 1.0, v29
	v_rcp_f32_e32 v28, v28
	v_rcp_f32_e32 v29, v29
	s_nop 0
	v_pk_mul_f32 v[28:29], v[30:31], v[28:29]
	s_nop 0
	v_pk_mul_f32 v[38:39], v[28:29], s[14:15] op_sel_hi:[1,0]
	v_cvt_pk_bf16_f32 v28, v32, v33
	v_cvt_pk_bf16_f32 v29, v34, v35
	v_cvt_pk_bf16_f32 v30, v36, v37
	v_cvt_pk_bf16_f32 v31, v38, v39
	ds_write_b128 v171, v[28:31] offset:272
	ds_read_b128 v[28:31], v147 offset:512
	ds_read_b128 v[32:35], v147 offset:528
	ds_read_b128 v[36:39], v148 offset:2048
	ds_read_b128 v[40:43], v148 offset:2064
	s_waitcnt lgkmcnt(1)
	v_pk_fma_f32 v[30:31], v[38:39], v[24:25], v[30:31]
	v_lshlrev_b32_e32 v24, 16, v26
	v_and_b32_e32 v25, 0xffff0000, v26
	v_lshlrev_b32_e32 v26, 16, v27
	v_and_b32_e32 v27, 0xffff0000, v27
	v_pk_fma_f32 v[36:37], v[36:37], v[44:45], v[28:29]
	s_waitcnt lgkmcnt(0)
	v_pk_fma_f32 v[34:35], v[42:43], v[26:27], v[34:35]
	ds_read_b128 v[26:29], v148 offset:2560
	v_pk_fma_f32 v[32:33], v[40:41], v[24:25], v[32:33]
	v_lshlrev_b32_e32 v24, 16, v20
	v_and_b32_e32 v25, 0xffff0000, v20
	v_lshlrev_b32_e32 v20, 16, v21
	v_and_b32_e32 v21, 0xffff0000, v21
	s_waitcnt lgkmcnt(0)
	v_pk_fma_f32 v[38:39], v[28:29], v[20:21], v[30:31]
	ds_read_b128 v[28:31], v148 offset:2576
	v_pk_fma_f32 v[36:37], v[26:27], v[24:25], v[36:37]
	v_lshlrev_b32_e32 v26, 16, v22
	v_and_b32_e32 v27, 0xffff0000, v22
	v_lshlrev_b32_e32 v22, 16, v23
	v_and_b32_e32 v23, 0xffff0000, v23
	s_waitcnt lgkmcnt(0)
	v_pk_fma_f32 v[40:41], v[30:31], v[22:23], v[34:35]
	v_pk_fma_f32 v[42:43], v[28:29], v[26:27], v[32:33]
	ds_read_b128 v[32:35], v148 offset:3072
	v_lshlrev_b32_e32 v28, 16, v16
	v_and_b32_e32 v29, 0xffff0000, v16
	v_lshlrev_b32_e32 v30, 16, v17
	v_and_b32_e32 v31, 0xffff0000, v17
	s_waitcnt lgkmcnt(0)
	v_pk_fma_f32 v[44:45], v[32:33], v[28:29], v[36:37]
	v_pk_fma_f32 v[46:47], v[34:35], v[30:31], v[38:39]
	ds_read_b128 v[32:35], v148 offset:3088
	v_lshlrev_b32_e32 v16, 16, v18
	v_and_b32_e32 v17, 0xffff0000, v18
	v_lshlrev_b32_e32 v18, 16, v19
	v_and_b32_e32 v19, 0xffff0000, v19
	s_waitcnt lgkmcnt(0)
	v_pk_fma_f32 v[48:49], v[34:35], v[18:19], v[40:41]
	ds_read_b128 v[38:41], v148 offset:3584
	v_lshlrev_b32_e32 v34, 16, v12
	v_and_b32_e32 v35, 0xffff0000, v12
	v_lshlrev_b32_e32 v36, 16, v13
	v_and_b32_e32 v37, 0xffff0000, v13
	s_waitcnt lgkmcnt(0)
	v_pk_fma_f32 v[46:47], v[40:41], v[36:37], v[46:47]
	v_pk_fma_f32 v[44:45], v[38:39], v[34:35], v[44:45]
	ds_read_b128 v[38:41], v148 offset:3600
	v_lshlrev_b32_e32 v12, 16, v15
	v_and_b32_e32 v13, 0xffff0000, v15
	v_pk_fma_f32 v[42:43], v[32:33], v[16:17], v[42:43]
	v_lshlrev_b32_e32 v32, 16, v14
	v_and_b32_e32 v33, 0xffff0000, v14
	s_waitcnt lgkmcnt(0)
	v_pk_fma_f32 v[14:15], v[40:41], v[12:13], v[48:49]
	v_mul_f32_e32 v40, 0xbfb8aa3b, v44
	v_mul_f32_e32 v41, 0xbfb8aa3b, v45
	v_exp_f32_e32 v40, v40
	v_exp_f32_e32 v41, v41
	v_pk_fma_f32 v[38:39], v[38:39], v[32:33], v[42:43]
	v_mul_f32_e32 v42, 0xbfb8aa3b, v46
	v_add_f32_e32 v40, 1.0, v40
	v_add_f32_e32 v41, 1.0, v41
	v_rcp_f32_e32 v40, v40
	v_rcp_f32_e32 v41, v41
	v_mul_f32_e32 v43, 0xbfb8aa3b, v47
	v_exp_f32_e32 v42, v42
	v_exp_f32_e32 v43, v43
	v_pk_mul_f32 v[40:41], v[44:45], v[40:41]
	v_mul_f32_e32 v44, 0xbfb8aa3b, v38
	v_mul_f32_e32 v45, 0xbfb8aa3b, v39
	v_exp_f32_e32 v44, v44
	v_exp_f32_e32 v45, v45
	v_add_f32_e32 v42, 1.0, v42
	v_add_f32_e32 v43, 1.0, v43
	v_add_f32_e32 v44, 1.0, v44
	v_add_f32_e32 v45, 1.0, v45
	v_rcp_f32_e32 v44, v44
	v_rcp_f32_e32 v45, v45
	v_rcp_f32_e32 v42, v42
	v_rcp_f32_e32 v43, v43
	v_pk_mul_f32 v[44:45], v[38:39], v[44:45]
	v_mul_f32_e32 v38, 0xbfb8aa3b, v14
	v_mul_f32_e32 v39, 0xbfb8aa3b, v15
	v_exp_f32_e32 v38, v38
	v_exp_f32_e32 v39, v39
	v_pk_mul_f32 v[42:43], v[46:47], v[42:43]
	v_add_f32_e32 v38, 1.0, v38
	v_add_f32_e32 v39, 1.0, v39
	v_rcp_f32_e32 v38, v38
	v_rcp_f32_e32 v39, v39
	s_nop 0
	v_pk_mul_f32 v[14:15], v[14:15], v[38:39]
	v_cvt_pk_bf16_f32 v38, v40, v41
	v_cvt_pk_bf16_f32 v39, v42, v43
	v_cvt_pk_bf16_f32 v40, v44, v45
	v_cvt_pk_bf16_f32 v41, v14, v15
	ds_write_b128 v171, v[38:41] offset:17408
	ds_read_b128 v[38:41], v147 offset:512
	ds_read_b128 v[42:45], v147 offset:528
	ds_read_b128 v[46:49], v148 offset:2048
	ds_read_b128 v[50:53], v148 offset:2064
	s_waitcnt lgkmcnt(1)
	v_pk_fma_f32 v[14:15], v[46:47], v[24:25], v[38:39]
	v_pk_fma_f32 v[24:25], v[48:49], v[20:21], v[40:41]
	s_waitcnt lgkmcnt(0)
	v_pk_fma_f32 v[38:39], v[52:53], v[22:23], v[44:45]
	ds_read_b128 v[20:23], v148 offset:2560
	v_pk_fma_f32 v[26:27], v[50:51], v[26:27], v[42:43]
	s_waitcnt lgkmcnt(0)
	v_pk_fma_f32 v[24:25], v[22:23], v[30:31], v[24:25]
	v_pk_fma_f32 v[28:29], v[20:21], v[28:29], v[14:15]
	ds_read_b128 v[20:23], v148 offset:2576
	s_waitcnt lgkmcnt(0)
	v_pk_fma_f32 v[20:21], v[20:21], v[16:17], v[26:27]
	ds_read_b128 v[14:17], v148 offset:3072
	v_pk_fma_f32 v[18:19], v[22:23], v[18:19], v[38:39]
	s_waitcnt lgkmcnt(0)
	v_pk_fma_f32 v[22:23], v[14:15], v[34:35], v[28:29]
	v_pk_fma_f32 v[24:25], v[16:17], v[36:37], v[24:25]
	ds_read_b128 v[14:17], v148 offset:3088
	s_waitcnt lgkmcnt(0)
	v_pk_fma_f32 v[20:21], v[14:15], v[32:33], v[20:21]
	v_pk_fma_f32 v[16:17], v[16:17], v[12:13], v[18:19]
	ds_read_b128 v[12:15], v148 offset:3584
	v_lshlrev_b32_e32 v18, 16, v8
	v_and_b32_e32 v19, 0xffff0000, v8
	v_lshlrev_b32_e32 v8, 16, v9
	v_and_b32_e32 v9, 0xffff0000, v9
	s_waitcnt lgkmcnt(0)
	v_pk_fma_f32 v[14:15], v[14:15], v[8:9], v[24:25]
	v_pk_fma_f32 v[12:13], v[12:13], v[18:19], v[22:23]
	v_lshlrev_b32_e32 v18, 16, v10
	v_and_b32_e32 v19, 0xffff0000, v10
	v_lshlrev_b32_e32 v22, 16, v11
	v_and_b32_e32 v23, 0xffff0000, v11
	ds_read_b128 v[8:11], v148 offset:3600
	s_waitcnt lgkmcnt(0)
	v_pk_fma_f32 v[10:11], v[10:11], v[22:23], v[16:17]
	v_mul_f32_e32 v16, 0xbfb8aa3b, v12
	v_mul_f32_e32 v17, 0xbfb8aa3b, v13
	v_exp_f32_e32 v16, v16
	v_exp_f32_e32 v17, v17
	v_pk_fma_f32 v[8:9], v[8:9], v[18:19], v[20:21]
	v_add_f32_e32 v16, 1.0, v16
	v_add_f32_e32 v17, 1.0, v17
	v_rcp_f32_e32 v16, v16
	v_rcp_f32_e32 v17, v17
	s_nop 0
	v_pk_mul_f32 v[12:13], v[12:13], v[16:17]
	v_mul_f32_e32 v16, 0xbfb8aa3b, v14
	v_mul_f32_e32 v17, 0xbfb8aa3b, v15
	v_exp_f32_e32 v16, v16
	v_exp_f32_e32 v17, v17
	v_add_f32_e32 v16, 1.0, v16
	v_add_f32_e32 v17, 1.0, v17
	v_rcp_f32_e32 v16, v16
	v_rcp_f32_e32 v17, v17
	s_nop 0
	v_pk_mul_f32 v[14:15], v[14:15], v[16:17]
	v_mul_f32_e32 v16, 0xbfb8aa3b, v8
	v_mul_f32_e32 v17, 0xbfb8aa3b, v9
	v_exp_f32_e32 v16, v16
	v_exp_f32_e32 v17, v17
	v_add_f32_e32 v16, 1.0, v16
	v_add_f32_e32 v17, 1.0, v17
	v_rcp_f32_e32 v16, v16
	v_rcp_f32_e32 v17, v17
	s_nop 0
	v_pk_mul_f32 v[16:17], v[8:9], v[16:17]
	v_mul_f32_e32 v8, 0xbfb8aa3b, v10
	v_mul_f32_e32 v9, 0xbfb8aa3b, v11
	v_exp_f32_e32 v8, v8
	v_exp_f32_e32 v9, v9
	v_add_f32_e32 v8, 1.0, v8
	v_add_f32_e32 v9, 1.0, v9
	v_rcp_f32_e32 v8, v8
	v_rcp_f32_e32 v9, v9
	s_nop 0
	v_pk_mul_f32 v[18:19], v[10:11], v[8:9]
	v_cvt_pk_bf16_f32 v8, v12, v13
	v_cvt_pk_bf16_f32 v9, v14, v15
	v_cvt_pk_bf16_f32 v10, v16, v17
	v_cvt_pk_bf16_f32 v11, v18, v19
	ds_write_b128 v171, v[8:11] offset:17680
	s_cbranch_vccnz .LBB0_546
	v_and_b32_e32 v8, 64, v216
	v_add_u32_e32 v9, -1, v216
	v_cmp_lt_i32_e32 vcc, v9, v8
	v_add_u32_e32 v11, -2, v216
	v_readlane_b32 s12, v254, 57
	v_cndmask_b32_e32 v9, v9, v216, vcc
	v_lshlrev_b32_e32 v9, 2, v9
	ds_bpermute_b32 v10, v9, v77
	v_cmp_lt_i32_e32 vcc, v11, v8
	v_readlane_b32 s13, v254, 58
	v_readlane_b32 s14, v254, 59
	v_cndmask_b32_e32 v11, v11, v216, vcc
	s_waitcnt lgkmcnt(0)
	v_add_f32_e32 v10, v77, v10
	v_cndmask_b32_e64 v10, v10, v77, s[48:49]
	v_lshlrev_b32_e32 v11, 2, v11
	ds_bpermute_b32 v12, v11, v10
	v_readlane_b32 s15, v254, 60
	v_readlane_b32 s16, v254, 61
	v_readlane_b32 s17, v254, 62
	v_readlane_b32 s18, v254, 63
	s_waitcnt lgkmcnt(0)
	v_add_f32_e32 v12, v10, v12
	v_cndmask_b32_e64 v10, v12, v10, s[12:13]
	v_add_u32_e32 v12, -4, v216
	v_cmp_lt_i32_e32 vcc, v12, v8
	v_readlane_b32 s19, v255, 0
	s_ashr_i32 s9, s8, 31
	v_cndmask_b32_e32 v12, v12, v216, vcc
	v_lshlrev_b32_e32 v12, 2, v12
	ds_bpermute_b32 v13, v12, v10
	s_waitcnt lgkmcnt(0)
	v_add_f32_e32 v13, v10, v13
	v_cndmask_b32_e64 v10, v13, v10, s[14:15]
	v_add_u32_e32 v13, -8, v216
	v_cmp_lt_i32_e32 vcc, v13, v8
	s_nop 1
	v_cndmask_b32_e32 v13, v13, v216, vcc
	v_lshlrev_b32_e32 v13, 2, v13
	ds_bpermute_b32 v14, v13, v10
	s_waitcnt lgkmcnt(0)
	v_add_f32_e32 v14, v10, v14
	v_cndmask_b32_e64 v10, v14, v10, s[16:17]
	v_add_u32_e32 v14, -16, v216
	v_cmp_lt_i32_e32 vcc, v14, v8
	s_nop 1
	v_cndmask_b32_e32 v14, v14, v216, vcc
	v_lshlrev_b32_e32 v14, 2, v14
	ds_bpermute_b32 v15, v14, v10
	s_waitcnt lgkmcnt(0)
	v_add_f32_e32 v15, v10, v15
	v_cndmask_b32_e64 v10, v15, v10, s[68:69]
	v_subrev_u32_e32 v15, 32, v216
	v_cmp_lt_i32_e32 vcc, v15, v8
	s_nop 1
	v_cndmask_b32_e32 v8, v15, v216, vcc
	v_lshlrev_b32_e32 v8, 2, v8
	ds_bpermute_b32 v15, v8, v10
	s_waitcnt lgkmcnt(0)
	v_add_f32_e32 v15, v10, v15
	v_cndmask_b32_e64 v10, v15, v10, s[18:19]
	v_sub_f32_e32 v15, v76, v10
	ds_bpermute_b32 v9, v9, v15
	ds_write2st64_b32 v149, v10, v15 offset1:1
	s_waitcnt lgkmcnt(1)
	v_max_f32_e32 v9, v9, v9
	v_max_f32_e32 v9, v15, v9
	v_cndmask_b32_e64 v9, v9, v15, s[48:49]
	ds_bpermute_b32 v11, v11, v9
	s_waitcnt lgkmcnt(0)
	v_max_f32_e32 v11, v11, v11
	v_max_f32_e32 v11, v9, v11
	v_cndmask_b32_e64 v9, v11, v9, s[12:13]
	ds_bpermute_b32 v11, v12, v9
	s_lshl_b64 s[12:13], s[8:9], 2
	v_readlane_b32 s9, v251, 53
	s_add_u32 s12, s9, s12
	v_readlane_b32 s9, v251, 54
	s_waitcnt lgkmcnt(0)
	v_max_f32_e32 v11, v11, v11
	v_max_f32_e32 v11, v9, v11
	v_cndmask_b32_e64 v9, v11, v9, s[14:15]
	ds_bpermute_b32 v11, v13, v9
	s_addc_u32 s13, s9, s13
	s_waitcnt lgkmcnt(0)
	v_max_f32_e32 v11, v11, v11
	v_max_f32_e32 v11, v9, v11
	v_cndmask_b32_e64 v9, v11, v9, s[16:17]
	ds_bpermute_b32 v11, v14, v9
	s_waitcnt lgkmcnt(0)
	v_max_f32_e32 v11, v11, v11
	v_max_f32_e32 v11, v9, v11
	v_cndmask_b32_e64 v9, v11, v9, s[68:69]
	ds_bpermute_b32 v8, v8, v9
	v_max_f32_e32 v11, v9, v9
	s_waitcnt lgkmcnt(0)
	v_max_f32_e32 v8, v8, v8
	v_max_f32_e32 v8, v11, v8
	v_cndmask_b32_e64 v8, v8, v9, s[18:19]
	global_load_dword v9, v181, s[12:13]
	v_max_f32_e32 v8, v8, v8
	s_waitcnt vmcnt(0)
	v_max_f32_e32 v11, v9, v9
	v_max_f32_e32 v8, v8, v11
	v_add_f32_e32 v8, v10, v8
	v_add_f32_e32 v9, v9, v10
	v_sub_f32_e32 v9, v9, v8
	v_mul_f32_e32 v9, 0x3fb8aa3b, v9
	v_exp_f32_e32 v9, v9
	ds_write2st64_b32 v149, v8, v9 offset0:2 offset1:3
	v_mul_f32_e32 v8, 0xbfb8aa3b, v8
	v_exp_f32_e32 v8, v8
	ds_write_b32 v149, v8 offset:1280

.LBB0_548:
	s_or_b64 exec, exec, s[12:13]
	v_or_b32_e32 v28, s52, v122
	s_waitcnt lgkmcnt(0)
	v_mov_b64_e32 v[24:25], s[4:5]
	s_movk_i32 s9, 0x1c00
	v_mad_u64_u32 v[24:25], s[12:13], v28, s9, v[24:25]
	s_mul_i32 s9, s53, 0x1c00
	v_add_u32_e32 v25, s9, v25
	v_lshl_add_u64 v[24:25], v[24:25], 0, s[90:91]
	s_mov_b64 s[12:13], 0x1800
	v_lshl_add_u64 v[30:31], v[24:25], 0, s[12:13]
	v_lshlrev_b64 v[32:33], 1, v[126:127]
	s_waitcnt lgkmcnt(0)
	s_barrier
	v_lshl_add_u64 v[24:25], v[30:31], 0, v[32:33]
	s_waitcnt vmcnt(0)
	v_mov_b32_e32 v34, v92
	v_mov_b32_e32 v35, v93
	s_lshl_b32 s9, s97, 2
	v_readlane_b32 s12, v255, 17
	s_add_u32 s12, s12, s9
	v_readlane_b32 s9, v255, 18
	s_addc_u32 s13, s9, 0
	v_lshl_add_u64 v[24:25], v[126:127], 2, s[12:13]
	v_mov_b32_e32 v24, v224
	v_mov_b32_e32 v25, v225
	v_mov_b32_e32 v26, v226
	v_mov_b32_e32 v27, v227
	ds_read2st64_b32 v[36:37], v158 offset1:1
	v_mov_b32_e32 v29, s53
	v_lshlrev_b64 v[28:29], 11, v[28:29]
	v_lshl_add_u64 v[28:29], s[20:21], 0, v[28:29]
	v_lshl_add_u64 v[28:29], v[28:29], 0, s[90:91]
	s_waitcnt lgkmcnt(0)
	v_add_f32_e32 v36, v36, v37
	v_fmamk_f32 v36, v36, 0x3c000000, v213
	v_rsq_f32_e32 v36, v36
	s_mov_b64 s[14:15], 0xc900400
	v_lshl_add_u64 v[28:29], v[28:29], 0, s[14:15]
	v_lshlrev_b64 v[38:39], 1, v[128:129]
	v_pk_mul_f32 v[22:23], v[22:23], v[36:37] op_sel_hi:[1,0]
	v_pk_mul_f32 v[20:21], v[20:21], v[36:37] op_sel_hi:[1,0]
	v_lshl_add_u64 v[32:33], v[28:29], 0, v[32:33]
	v_lshl_add_u64 v[40:41], v[30:31], 0, v[38:39]
	v_lshlrev_b32_e32 v37, 16, v34
	v_and_b32_e32 v34, 0xffff0000, v34
	v_lshlrev_b32_e32 v42, 16, v35
	v_and_b32_e32 v35, 0xffff0000, v35
	v_mul_f32_e32 v37, 0xbfb8aa3b, v37
	v_mul_f32_e32 v34, 0xbfb8aa3b, v34
	v_mul_f32_e32 v42, 0xbfb8aa3b, v42
	v_mul_f32_e32 v35, 0xbfb8aa3b, v35
	v_exp_f32_e32 v37, v37
	v_exp_f32_e32 v34, v34
	v_exp_f32_e32 v42, v42
	v_exp_f32_e32 v35, v35
	v_add_f32_e32 v37, 1.0, v37
	v_add_f32_e32 v43, 1.0, v34
	v_add_f32_e32 v42, 1.0, v42
	v_add_f32_e32 v44, 1.0, v35
	v_rcp_f32_e32 v34, v37
	v_rcp_f32_e32 v35, v43
	v_rcp_f32_e32 v42, v42
	v_rcp_f32_e32 v43, v44
	s_waitcnt vmcnt(0)
	v_pk_mul_f32 v[22:23], v[24:25], v[22:23]
	v_pk_mul_f32 v[20:21], v[26:27], v[20:21]
	v_pk_mul_f32 v[22:23], v[22:23], v[34:35]
	v_pk_mul_f32 v[20:21], v[20:21], v[42:43]
	v_cvt_pk_bf16_f32 v22, v22, v23
	v_cvt_pk_bf16_f32 v23, v20, v21
	global_store_dwordx2 v[32:33], v[22:23], off
	v_mov_b32_e32 v24, v94
	v_mov_b32_e32 v25, v95
	v_mov_b32_e32 v34, v96
	v_mov_b32_e32 v35, v97
	v_lshl_add_u64 v[26:27], v[128:129], 2, s[12:13]
	v_mov_b32_e32 v20, v228
	v_mov_b32_e32 v21, v229
	v_mov_b32_e32 v22, v230
	v_mov_b32_e32 v23, v231
	v_lshl_add_u64 v[32:33], v[28:29], 0, v[38:39]
	v_pk_mul_f32 v[18:19], v[18:19], v[36:37] op_sel_hi:[1,0]
	v_pk_mul_f32 v[16:17], v[16:17], v[36:37] op_sel_hi:[1,0]
	v_lshlrev_b32_e32 v37, 16, v24
	v_and_b32_e32 v24, 0xffff0000, v24
	v_lshlrev_b32_e32 v38, 16, v25
	v_and_b32_e32 v25, 0xffff0000, v25
	v_mul_f32_e32 v37, 0xbfb8aa3b, v37
	v_mul_f32_e32 v24, 0xbfb8aa3b, v24
	v_mul_f32_e32 v38, 0xbfb8aa3b, v38
	v_mul_f32_e32 v25, 0xbfb8aa3b, v25
	v_exp_f32_e32 v37, v37
	v_exp_f32_e32 v24, v24
	v_exp_f32_e32 v38, v38
	v_exp_f32_e32 v25, v25
	v_add_f32_e32 v37, 1.0, v37
	v_add_f32_e32 v39, 1.0, v24
	v_add_f32_e32 v38, 1.0, v38
	v_add_f32_e32 v40, 1.0, v25
	v_rcp_f32_e32 v24, v37
	v_rcp_f32_e32 v25, v39
	v_rcp_f32_e32 v38, v38
	v_rcp_f32_e32 v39, v40
	s_waitcnt vmcnt(0)
	v_pk_mul_f32 v[18:19], v[18:19], v[20:21]
	v_pk_mul_f32 v[16:17], v[16:17], v[22:23]
	v_pk_mul_f32 v[18:19], v[18:19], v[24:25]
	v_pk_mul_f32 v[16:17], v[16:17], v[38:39]
	v_cvt_pk_bf16_f32 v18, v18, v19
	v_cvt_pk_bf16_f32 v19, v16, v17
	global_store_dwordx2 v[32:33], v[18:19], off offset:32
	v_mov_b32_e32 v16, v232
	v_mov_b32_e32 v17, v233
	v_mov_b32_e32 v18, v234
	v_mov_b32_e32 v19, v235
	v_lshlrev_b32_e32 v24, 16, v34
	v_and_b32_e32 v25, 0xffff0000, v34
	v_lshlrev_b32_e32 v26, 16, v35
	v_and_b32_e32 v27, 0xffff0000, v35
	v_mul_f32_e32 v24, 0xbfb8aa3b, v24
	v_mul_f32_e32 v25, 0xbfb8aa3b, v25
	v_mul_f32_e32 v26, 0xbfb8aa3b, v26
	v_mul_f32_e32 v27, 0xbfb8aa3b, v27
	v_exp_f32_e32 v24, v24
	v_exp_f32_e32 v25, v25
	v_exp_f32_e32 v26, v26
	v_exp_f32_e32 v27, v27
	v_add_f32_e32 v24, 1.0, v24
	v_add_f32_e32 v25, 1.0, v25
	v_add_f32_e32 v26, 1.0, v26
	v_add_f32_e32 v27, 1.0, v27
	v_rcp_f32_e32 v24, v24
	v_rcp_f32_e32 v25, v25
	v_rcp_f32_e32 v26, v26
	v_rcp_f32_e32 v27, v27
	v_pk_mul_f32 v[14:15], v[14:15], v[36:37] op_sel_hi:[1,0]
	v_pk_mul_f32 v[12:13], v[12:13], v[36:37] op_sel_hi:[1,0]
	v_lshlrev_b64 v[20:21], 1, v[124:125]
	v_lshl_add_u64 v[22:23], v[30:31], 0, v[20:21]
	v_pk_mul_f32 v[10:11], v[10:11], v[36:37] op_sel_hi:[1,0]
	v_pk_mul_f32 v[8:9], v[8:9], v[36:37] op_sel_hi:[1,0]
	s_waitcnt vmcnt(0)
	v_pk_mul_f32 v[14:15], v[14:15], v[16:17]
	v_pk_mul_f32 v[12:13], v[12:13], v[18:19]
	v_pk_mul_f32 v[14:15], v[14:15], v[24:25]
	v_pk_mul_f32 v[12:13], v[12:13], v[26:27]
	v_cvt_pk_bf16_f32 v14, v14, v15
	v_cvt_pk_bf16_f32 v15, v12, v13
	global_store_dwordx2 v[32:33], v[14:15], off offset:64
	v_mov_b32_e32 v16, v98
	v_mov_b32_e32 v17, v99
	v_lshl_add_u64 v[12:13], v[124:125], 2, s[12:13]
	v_mov_b32_e32 v12, v236
	v_mov_b32_e32 v13, v237
	v_mov_b32_e32 v14, v238
	v_mov_b32_e32 v15, v239
	v_lshl_add_u64 v[18:19], v[28:29], 0, v[20:21]
	s_mov_b64 s[12:13], 0
	v_lshlrev_b32_e32 v20, 16, v16
	v_and_b32_e32 v16, 0xffff0000, v16
	v_lshlrev_b32_e32 v21, 16, v17
	v_and_b32_e32 v17, 0xffff0000, v17
	v_mul_f32_e32 v20, 0xbfb8aa3b, v20
	v_mul_f32_e32 v16, 0xbfb8aa3b, v16
	v_mul_f32_e32 v21, 0xbfb8aa3b, v21
	v_mul_f32_e32 v17, 0xbfb8aa3b, v17
	v_exp_f32_e32 v20, v20
	v_exp_f32_e32 v16, v16
	v_exp_f32_e32 v21, v21
	v_exp_f32_e32 v17, v17
	v_add_f32_e32 v20, 1.0, v20
	v_add_f32_e32 v22, 1.0, v16
	v_add_f32_e32 v21, 1.0, v21
	v_add_f32_e32 v23, 1.0, v17
	v_rcp_f32_e32 v16, v20
	v_rcp_f32_e32 v17, v22
	v_rcp_f32_e32 v20, v21
	v_rcp_f32_e32 v21, v23
	s_waitcnt vmcnt(0)
	v_pk_mul_f32 v[10:11], v[10:11], v[12:13]
	v_pk_mul_f32 v[8:9], v[8:9], v[14:15]
	v_pk_mul_f32 v[10:11], v[10:11], v[16:17]
	v_pk_mul_f32 v[8:9], v[8:9], v[20:21]
	v_cvt_pk_bf16_f32 v10, v10, v11
	v_cvt_pk_bf16_f32 v11, v8, v9
	global_store_dwordx2 v[18:19], v[10:11], off
	s_waitcnt lgkmcnt(0)
	s_barrier
